# FN 5,13,16: additionally the L0 w_out residual phase (latent and context tiles) applies the L0 ffn norm in its epilogue; phase 6 skipped
# baseline (speedup 1.0000x reference)
; #define GAS __attribute__((address_space(1)))
; template <class T> __device__ __forceinline__ GAS T* gptr(T* q) { return (GAS T*)(unsigned long long)uptr(q); }
; __device__ __forceinline__ void gemm_epilogue(LAS unsigned char* lds, const GD& gd, const f32x4 (&acc)[2][2][4][2], const Unit& u) {
;     ...
;     if (mode == M_RES) {
;         const bool lat = row_u < NL;
;         const int rb = lat ? (row_u >> 12) : 4;
;         GAS const float* gmr = gptr(gd.gm + rb * 6144 + u.pn * BM);
;         GAS const float* xin = gptr((lat ? gd.xin_lat : gd.xin_ctx - (size_t)NL * DM) + (size_t)row_u * DM + u.pn * BM);
;         GAS float* xout = gptr((lat ? gd.xout_lat : gd.xout_ctx - (size_t)NL * DM) + (size_t)row_u * DM + u.pn * BM);
.LBB0_395:
	s_andn2_b64 vcc, exec, s[4:5]
	s_cbranch_vccnz .LBB0_397
	s_cmpk_lg_u32 s72, 0x100
	s_cbranch_scc1 .Lmy_fn_orig
	v_readlane_b32 s2, v255, 0
	s_nop 3
	s_cmp_lg_u32 s17, 8
	s_cbranch_scc1 .Lmy_fn_c1
	s_cmp_lg_u32 s2, 1
	s_cbranch_scc1 .Lmy_fn_c1
	s_mov_b32 s92, 0
	s_movk_i32 s93, 12
	s_branch .Lmy_fn_go
.Lmy_fn_c1:
	s_cmp_lg_u32 s17, 4
	s_cbranch_scc1 .Lmy_fn_c2
	s_cmp_lg_u32 s2, 1
	s_cbranch_scc1 .Lmy_fn_c2
	s_mov_b32 s92, 1
	s_movk_i32 s93, 8
	s_mov_b32 s94, 135168
	s_movk_i32 s95, 4096
	s_movk_i32 s32, 8
	s_branch .Lmy_fn_go
.Lmy_fn_c2:
	s_cmp_lg_u32 s17, 4
	s_cbranch_scc1 .Lmy_fn_c3
	s_cmp_lg_u32 s2, 0
	s_cbranch_scc1 .Lmy_fn_c3
	s_mov_b32 s92, 1
	s_movk_i32 s93, 4
	s_movk_i32 s94, 0x3000
	s_movk_i32 s95, 0
	s_movk_i32 s32, 8
	s_branch .Lmy_fn_go

; __global__ void __launch_bounds__(512) mega(Params pk) {
;     ...
;     for (int ph = ph_lo; ph < ph_hi; ++ph) {
;         const int l = (ph - 1) / 8, sub = (ph == 0) ? 9 : (((ph - 1) % 8) == 7 ? 8 : (ph - 1) % 8);
;         int nrep = 1;
;     ...
;         if (ph < N_PHASES - 1 && sub == (PROBE % 100)) nrep = 2;
;     ...
;         for (int rep = 0; rep < nrep; ++rep) {
;             const bool dry = (PROBE >= 200) && (rep == 0) && (nrep == 2);
;             if (ph == 0) { const Params p = load_params(lp); phase_prep(p, lds); }
;             else if (ph == N_PHASES - 1) { const Params p = load_params(lp); phase_final(p); }
;             else if (sub == 0 || sub == 5) { const Params p = load_params(lp); phase_norm(p, l, sub == 5); }
;             else if (sub == 2) { const Params p = load_params(lp); phase_mix(p, l, lds); }
;             else { for (int gi = 0; gi < 6; ++gi) { if (!gemm_phase(lds, l, sub, gi, dry)) break; } }
;             if (rep + 1 < nrep) xcd_barrier(xb);
;         }
;         if (ph + 1 < ph_hi) xcd_barrier(xb);
;         if (ph_hi > 1000) grid.sync();
;     }
.LBB0_735:
	s_cmpk_lg_u32 s72, 0x100
	s_cbranch_scc1 .Lmy_fn_nsk
	s_cmp_eq_u32 s16, 5
	s_cbranch_scc1 .Lmy_fn_sk
	s_cmp_eq_u32 s16, 13
	s_cbranch_scc1 .Lmy_fn_sk
	s_cmp_eq_u32 s16, 16
	s_cbranch_scc1 .Lmy_fn_sk
	s_branch .Lmy_fn_nsk
